# adaLN loads batched (silu staging, 64 w_ada loads up front) + half of the workgroups (bit 3, ids >= 32) start the in-proj GEMM 12 us later to desynchronize the epilogue store bursts
# speedup vs baseline: 1.0188x; 1.0075x over previous
.LBB0_23:
	global_load_dword v210, v[4:5], off
	global_load_dword v211, v[4:5], off offset:2048
	v_lshl_add_u64 v[244:245], v[6:7], 2, s[22:23]
	s_mov_b64 s[12:13], 0x1000
	v_lshl_add_u64 v[244:245], v[244:245], 0, s[12:13]
	global_load_dword v212, v[244:245], off offset:-4096
	global_load_dword v213, v[244:245], off offset:-2048
	global_load_dword v214, v[244:245], off
	global_load_dword v215, v[244:245], off offset:2048
	s_mov_b64 s[12:13], 0x2000
	v_lshl_add_u64 v[244:245], v[244:245], 0, s[12:13]
	global_load_dword v216, v[244:245], off offset:-4096
	global_load_dword v217, v[244:245], off offset:-2048
	global_load_dword v218, v[244:245], off
	global_load_dword v219, v[244:245], off offset:2048
	s_waitcnt vmcnt(9)
	v_mul_f32_e32 v9, 0xbfb8aa3b, v210
	v_exp_f32_e32 v9, v9
	s_nop 0
	v_add_f32_e32 v8, 1.0, v9
	v_rcp_f32_e32 v9, v8
	s_nop 0
	v_mul_f32_e32 v210, v210, v9
	ds_write_b32 v1, v210
	s_waitcnt vmcnt(8)
	v_mul_f32_e32 v9, 0xbfb8aa3b, v211
	v_exp_f32_e32 v9, v9
	s_nop 0
	v_add_f32_e32 v8, 1.0, v9
	v_rcp_f32_e32 v9, v8
	s_nop 0
	v_mul_f32_e32 v211, v211, v9
	ds_write_b32 v1, v211 offset:2048
	s_waitcnt vmcnt(7)
	v_mul_f32_e32 v9, 0xbfb8aa3b, v212
	v_exp_f32_e32 v9, v9
	s_nop 0
	v_add_f32_e32 v8, 1.0, v9
	v_rcp_f32_e32 v9, v8
	s_nop 0
	v_mul_f32_e32 v212, v212, v9
	ds_write_b32 v1, v212 offset:4096
	s_waitcnt vmcnt(6)
	v_mul_f32_e32 v9, 0xbfb8aa3b, v213
	v_exp_f32_e32 v9, v9
	s_nop 0
	v_add_f32_e32 v8, 1.0, v9
	v_rcp_f32_e32 v9, v8
	s_nop 0
	v_mul_f32_e32 v213, v213, v9
	ds_write_b32 v1, v213 offset:6144
	s_waitcnt vmcnt(5)
	v_mul_f32_e32 v9, 0xbfb8aa3b, v214
	v_exp_f32_e32 v9, v9
	s_nop 0
	v_add_f32_e32 v8, 1.0, v9
	v_rcp_f32_e32 v9, v8
	s_nop 0
	v_mul_f32_e32 v214, v214, v9
	ds_write_b32 v1, v214 offset:8192
	s_waitcnt vmcnt(4)
	v_mul_f32_e32 v9, 0xbfb8aa3b, v215
	v_exp_f32_e32 v9, v9
	s_nop 0
	v_add_f32_e32 v8, 1.0, v9
	v_rcp_f32_e32 v9, v8
	s_nop 0
	v_mul_f32_e32 v215, v215, v9
	ds_write_b32 v1, v215 offset:10240
	s_waitcnt vmcnt(3)
	v_mul_f32_e32 v9, 0xbfb8aa3b, v216
	v_exp_f32_e32 v9, v9
	s_nop 0
	v_add_f32_e32 v8, 1.0, v9
	v_rcp_f32_e32 v9, v8
	s_nop 0
	v_mul_f32_e32 v216, v216, v9
	ds_write_b32 v1, v216 offset:12288
	s_waitcnt vmcnt(2)
	v_mul_f32_e32 v9, 0xbfb8aa3b, v217
	v_exp_f32_e32 v9, v9
	s_nop 0
	v_add_f32_e32 v8, 1.0, v9
	v_rcp_f32_e32 v9, v8
	s_nop 0
	v_mul_f32_e32 v217, v217, v9
	ds_write_b32 v1, v217 offset:14336
	s_waitcnt vmcnt(1)
	v_mul_f32_e32 v9, 0xbfb8aa3b, v218
	v_exp_f32_e32 v9, v9
	s_nop 0
	v_add_f32_e32 v8, 1.0, v9
	v_rcp_f32_e32 v9, v8
	s_nop 0
	v_mul_f32_e32 v218, v218, v9
	ds_write_b32 v1, v218 offset:16384
	s_waitcnt vmcnt(0)
	v_mul_f32_e32 v9, 0xbfb8aa3b, v219
	v_exp_f32_e32 v9, v9
	s_nop 0
	v_add_f32_e32 v8, 1.0, v9
	v_rcp_f32_e32 v9, v8
	s_nop 0
	v_mul_f32_e32 v219, v219, v9
	ds_write_b32 v1, v219 offset:18432

.LBB0_26:
	s_mov_b64 s[12:13], 0x60000
	v_add_co_u32_e32 v244, vcc, 0xffd60000, v6
	s_nop 1
	v_addc_co_u32_e32 v245, vcc, -1, v7, vcc
	global_load_dword v178, v[244:245], off
	v_lshl_add_u64 v[244:245], v[244:245], 0, s[12:13]
	global_load_dword v179, v[244:245], off
	v_lshl_add_u64 v[244:245], v[244:245], 0, s[12:13]
	global_load_dword v180, v[244:245], off
	v_lshl_add_u64 v[244:245], v[244:245], 0, s[12:13]
	global_load_dword v181, v[244:245], off
	v_lshl_add_u64 v[244:245], v[244:245], 0, s[12:13]
	global_load_dword v182, v[244:245], off
	v_lshl_add_u64 v[244:245], v[244:245], 0, s[12:13]
	global_load_dword v183, v[244:245], off
	v_lshl_add_u64 v[244:245], v[244:245], 0, s[12:13]
	global_load_dword v184, v[244:245], off
	v_lshl_add_u64 v[244:245], v[244:245], 0, s[12:13]
	global_load_dword v185, v[244:245], off
	v_lshl_add_u64 v[244:245], v[244:245], 0, s[12:13]
	global_load_dword v186, v[244:245], off
	v_lshl_add_u64 v[244:245], v[244:245], 0, s[12:13]
	global_load_dword v187, v[244:245], off
	v_lshl_add_u64 v[244:245], v[244:245], 0, s[12:13]
	global_load_dword v188, v[244:245], off
	v_lshl_add_u64 v[244:245], v[244:245], 0, s[12:13]
	global_load_dword v189, v[244:245], off
	v_lshl_add_u64 v[244:245], v[244:245], 0, s[12:13]
	global_load_dword v190, v[244:245], off
	v_lshl_add_u64 v[244:245], v[244:245], 0, s[12:13]
	global_load_dword v191, v[244:245], off
	v_lshl_add_u64 v[244:245], v[244:245], 0, s[12:13]
	global_load_dword v192, v[244:245], off
	v_lshl_add_u64 v[244:245], v[244:245], 0, s[12:13]
	global_load_dword v193, v[244:245], off
	v_lshl_add_u64 v[244:245], v[244:245], 0, s[12:13]
	global_load_dword v194, v[244:245], off
	v_lshl_add_u64 v[244:245], v[244:245], 0, s[12:13]
	global_load_dword v195, v[244:245], off
	v_lshl_add_u64 v[244:245], v[244:245], 0, s[12:13]
	global_load_dword v196, v[244:245], off
	v_lshl_add_u64 v[244:245], v[244:245], 0, s[12:13]
	global_load_dword v197, v[244:245], off
	v_lshl_add_u64 v[244:245], v[244:245], 0, s[12:13]
	global_load_dword v198, v[244:245], off
	v_lshl_add_u64 v[244:245], v[244:245], 0, s[12:13]
	global_load_dword v199, v[244:245], off
	v_lshl_add_u64 v[244:245], v[244:245], 0, s[12:13]
	global_load_dword v200, v[244:245], off
	v_lshl_add_u64 v[244:245], v[244:245], 0, s[12:13]
	global_load_dword v201, v[244:245], off
	v_lshl_add_u64 v[244:245], v[244:245], 0, s[12:13]
	global_load_dword v204, v[244:245], off
	v_lshl_add_u64 v[244:245], v[244:245], 0, s[12:13]
	global_load_dword v205, v[244:245], off
	v_lshl_add_u64 v[244:245], v[244:245], 0, s[12:13]
	global_load_dword v206, v[244:245], off
	v_lshl_add_u64 v[244:245], v[244:245], 0, s[12:13]
	global_load_dword v207, v[244:245], off
	v_lshl_add_u64 v[244:245], v[244:245], 0, s[12:13]
	global_load_dword v208, v[244:245], off
	v_lshl_add_u64 v[244:245], v[244:245], 0, s[12:13]
	global_load_dword v209, v[244:245], off
	v_lshl_add_u64 v[244:245], v[244:245], 0, s[12:13]
	global_load_dword v210, v[244:245], off
	v_lshl_add_u64 v[244:245], v[244:245], 0, s[12:13]
	global_load_dword v211, v[244:245], off
	v_lshl_add_u64 v[244:245], v[244:245], 0, s[12:13]
	global_load_dword v212, v[244:245], off
	v_lshl_add_u64 v[244:245], v[244:245], 0, s[12:13]
	global_load_dword v213, v[244:245], off
	v_lshl_add_u64 v[244:245], v[244:245], 0, s[12:13]
	global_load_dword v214, v[244:245], off
	v_lshl_add_u64 v[244:245], v[244:245], 0, s[12:13]
	global_load_dword v215, v[244:245], off
	v_lshl_add_u64 v[244:245], v[244:245], 0, s[12:13]
	global_load_dword v216, v[244:245], off
	v_lshl_add_u64 v[244:245], v[244:245], 0, s[12:13]
	global_load_dword v217, v[244:245], off
	v_lshl_add_u64 v[244:245], v[244:245], 0, s[12:13]
	global_load_dword v218, v[244:245], off
	v_lshl_add_u64 v[244:245], v[244:245], 0, s[12:13]
	global_load_dword v219, v[244:245], off
	v_lshl_add_u64 v[244:245], v[244:245], 0, s[12:13]
	global_load_dword v220, v[244:245], off
	v_lshl_add_u64 v[244:245], v[244:245], 0, s[12:13]
	global_load_dword v221, v[244:245], off
	v_lshl_add_u64 v[244:245], v[244:245], 0, s[12:13]
	global_load_dword v222, v[244:245], off
	v_lshl_add_u64 v[244:245], v[244:245], 0, s[12:13]
	global_load_dword v223, v[244:245], off
	v_lshl_add_u64 v[244:245], v[244:245], 0, s[12:13]
	global_load_dword v224, v[244:245], off
	v_lshl_add_u64 v[244:245], v[244:245], 0, s[12:13]
	global_load_dword v225, v[244:245], off
	v_lshl_add_u64 v[244:245], v[244:245], 0, s[12:13]
	global_load_dword v226, v[244:245], off
	v_lshl_add_u64 v[244:245], v[244:245], 0, s[12:13]
	global_load_dword v227, v[244:245], off
	v_lshl_add_u64 v[244:245], v[244:245], 0, s[12:13]
	global_load_dword v228, v[244:245], off
	v_lshl_add_u64 v[244:245], v[244:245], 0, s[12:13]
	global_load_dword v229, v[244:245], off
	v_lshl_add_u64 v[244:245], v[244:245], 0, s[12:13]
	global_load_dword v230, v[244:245], off
	v_lshl_add_u64 v[244:245], v[244:245], 0, s[12:13]
	global_load_dword v231, v[244:245], off
	v_lshl_add_u64 v[244:245], v[244:245], 0, s[12:13]
	global_load_dword v232, v[244:245], off
	v_lshl_add_u64 v[244:245], v[244:245], 0, s[12:13]
	global_load_dword v233, v[244:245], off
	v_lshl_add_u64 v[244:245], v[244:245], 0, s[12:13]
	global_load_dword v234, v[244:245], off
	v_lshl_add_u64 v[244:245], v[244:245], 0, s[12:13]
	global_load_dword v235, v[244:245], off
	v_lshl_add_u64 v[244:245], v[244:245], 0, s[12:13]
	global_load_dword v236, v[244:245], off
	v_lshl_add_u64 v[244:245], v[244:245], 0, s[12:13]
	global_load_dword v237, v[244:245], off
	v_lshl_add_u64 v[244:245], v[244:245], 0, s[12:13]
	global_load_dword v238, v[244:245], off
	v_lshl_add_u64 v[244:245], v[244:245], 0, s[12:13]
	global_load_dword v239, v[244:245], off
	v_lshl_add_u64 v[244:245], v[244:245], 0, s[12:13]
	global_load_dword v240, v[244:245], off
	v_lshl_add_u64 v[244:245], v[244:245], 0, s[12:13]
	global_load_dword v241, v[244:245], off
	v_lshl_add_u64 v[244:245], v[244:245], 0, s[12:13]
	global_load_dword v242, v[244:245], off
	v_lshl_add_u64 v[244:245], v[244:245], 0, s[12:13]
	global_load_dword v243, v[244:245], off
	ds_read2_b32 v[20:21], v18 offset1:16
	v_add_u32_e32 v54, 0x1000, v18
	v_add_u32_e32 v62, 0x4000, v18
	s_waitcnt lgkmcnt(0)
	v_mov_b32_e32 v64, v20
	ds_read2_b32 v[26:27], v18 offset0:32 offset1:48
	ds_read2_b32 v[28:29], v18 offset0:64 offset1:80
	ds_read2_b32 v[30:31], v18 offset0:96 offset1:112
	v_add_u32_e32 v17, 0x2000, v18
	v_add_u32_e32 v23, 0x3000, v18
	ds_read2_b32 v[32:33], v54 offset1:16
	ds_read2_b32 v[34:35], v17 offset1:16
	ds_read2_b32 v[36:37], v23 offset1:16
	ds_read2_b32 v[38:39], v62 offset1:16
	ds_read2_b32 v[40:41], v54 offset0:32 offset1:48
	ds_read2_b32 v[42:43], v17 offset0:32 offset1:48
	ds_read2_b32 v[44:45], v23 offset0:32 offset1:48
	ds_read2_b32 v[46:47], v62 offset0:32 offset1:48
	ds_read2_b32 v[48:49], v54 offset0:64 offset1:80
	ds_read2_b32 v[50:51], v17 offset0:64 offset1:80
	ds_read2_b32 v[52:53], v23 offset0:64 offset1:80
	ds_read2_b32 v[54:55], v54 offset0:96 offset1:112
	ds_read2_b32 v[56:57], v17 offset0:96 offset1:112
	ds_read2_b32 v[58:59], v23 offset0:96 offset1:112
	ds_read2_b32 v[60:61], v62 offset0:64 offset1:80
	ds_read2_b32 v[62:63], v62 offset0:96 offset1:112
	s_waitcnt lgkmcnt(14)
	v_mov_b32_e32 v20, v26
	v_mov_b32_e32 v26, v28
	v_mov_b32_e32 v28, v30
	v_mov_b32_e32 v65, v32
	v_mov_b32_e32 v32, v21
	s_waitcnt lgkmcnt(11)
	v_mov_b32_e32 v21, v40
	v_mov_b32_e32 v40, v27
	s_waitcnt lgkmcnt(7)
	v_mov_b32_e32 v27, v48
	v_mov_b32_e32 v48, v29
	s_waitcnt lgkmcnt(4)
	v_mov_b32_e32 v29, v54
	v_mov_b32_e32 v54, v31
	v_mov_b32_e32 v30, v34
	v_mov_b32_e32 v31, v36
	v_mov_b32_e32 v36, v35
	v_mov_b32_e32 v34, v42
	v_mov_b32_e32 v42, v50
	s_waitcnt lgkmcnt(3)
	v_mov_b32_e32 v50, v56
	v_mov_b32_e32 v35, v44
	v_mov_b32_e32 v44, v43
	v_mov_b32_e32 v43, v52
	v_mov_b32_e32 v52, v51
	s_waitcnt lgkmcnt(2)
	v_mov_b32_e32 v51, v58
	v_mov_b32_e32 v58, v57
	v_add_u32_e32 v18, 0x200, v18
	s_waitcnt vmcnt(56)
	v_mov_b32_e32 v12, v178
	v_mov_b32_e32 v13, v179
	v_mov_b32_e32 v14, v180
	v_mov_b32_e32 v15, v181
	v_mov_b32_e32 v24, v182
	v_mov_b32_e32 v25, v183
	v_mov_b32_e32 v16, v184
	v_mov_b32_e32 v22, v185
	v_pk_fma_f32 v[10:11], v[12:13], v[64:65], v[10:11] op_sel_hi:[0,1,1]
	v_mov_b32_e32 v56, v13
	v_pk_fma_f32 v[8:9], v[12:13], v[30:31], v[8:9] op_sel_hi:[0,1,1]
	v_pk_mul_f32 v[38:39], v[12:13], v[38:39]
	v_pk_fma_f32 v[10:11], v[56:57], v[32:33], v[10:11] op_sel_hi:[0,1,1]
	v_pk_fma_f32 v[8:9], v[56:57], v[36:37], v[8:9] op_sel_hi:[0,1,1]
	v_add_f32_e32 v5, v5, v38
	v_add_f32_e32 v5, v5, v39
	v_pk_fma_f32 v[10:11], v[14:15], v[20:21], v[10:11] op_sel_hi:[0,1,1]
	v_mov_b32_e32 v20, v15
	v_pk_fma_f32 v[8:9], v[14:15], v[34:35], v[8:9] op_sel_hi:[0,1,1]
	v_pk_mul_f32 v[12:13], v[14:15], v[46:47]
	v_pk_fma_f32 v[10:11], v[20:21], v[40:41], v[10:11] op_sel_hi:[0,1,1]
	v_pk_fma_f32 v[8:9], v[20:21], v[44:45], v[8:9] op_sel_hi:[0,1,1]
	v_add_f32_e32 v5, v5, v12
	v_add_f32_e32 v5, v5, v13
	v_pk_fma_f32 v[10:11], v[24:25], v[26:27], v[10:11] op_sel_hi:[0,1,1]
	v_mov_b32_e32 v14, v25
	v_pk_fma_f32 v[8:9], v[24:25], v[42:43], v[8:9] op_sel_hi:[0,1,1]
	s_waitcnt lgkmcnt(1)
	v_pk_mul_f32 v[12:13], v[24:25], v[60:61]
	v_pk_fma_f32 v[10:11], v[14:15], v[48:49], v[10:11] op_sel_hi:[0,1,1]
	v_pk_fma_f32 v[8:9], v[14:15], v[52:53], v[8:9] op_sel_hi:[0,1,1]
	v_add_f32_e32 v5, v5, v12
	v_pk_fma_f32 v[10:11], v[16:17], v[28:29], v[10:11] op_sel_hi:[0,1,1]
	v_pk_fma_f32 v[8:9], v[16:17], v[50:51], v[8:9] op_sel_hi:[0,1,1]
	v_mov_b32_e32 v17, v22
	v_add_f32_e32 v5, v5, v13
	s_waitcnt lgkmcnt(0)
	v_pk_mul_f32 v[12:13], v[16:17], v[62:63]
	v_pk_fma_f32 v[10:11], v[22:23], v[54:55], v[10:11] op_sel_hi:[0,1,1]
	v_add_f32_e32 v5, v5, v12
	v_pk_fma_f32 v[8:9], v[22:23], v[58:59], v[8:9] op_sel_hi:[0,1,1]
	v_add_f32_e32 v5, v5, v13
	ds_read2_b32 v[20:21], v18 offset1:16
	v_add_u32_e32 v54, 0x1000, v18
	v_add_u32_e32 v62, 0x4000, v18
	s_waitcnt lgkmcnt(0)
	v_mov_b32_e32 v64, v20
	ds_read2_b32 v[26:27], v18 offset0:32 offset1:48
	ds_read2_b32 v[28:29], v18 offset0:64 offset1:80
	ds_read2_b32 v[30:31], v18 offset0:96 offset1:112
	v_add_u32_e32 v17, 0x2000, v18
	v_add_u32_e32 v23, 0x3000, v18
	ds_read2_b32 v[32:33], v54 offset1:16
	ds_read2_b32 v[34:35], v17 offset1:16
	ds_read2_b32 v[36:37], v23 offset1:16
	ds_read2_b32 v[38:39], v62 offset1:16
	ds_read2_b32 v[40:41], v54 offset0:32 offset1:48
	ds_read2_b32 v[42:43], v17 offset0:32 offset1:48
	ds_read2_b32 v[44:45], v23 offset0:32 offset1:48
	ds_read2_b32 v[46:47], v62 offset0:32 offset1:48
	ds_read2_b32 v[48:49], v54 offset0:64 offset1:80
	ds_read2_b32 v[50:51], v17 offset0:64 offset1:80
	ds_read2_b32 v[52:53], v23 offset0:64 offset1:80
	ds_read2_b32 v[54:55], v54 offset0:96 offset1:112
	ds_read2_b32 v[56:57], v17 offset0:96 offset1:112
	ds_read2_b32 v[58:59], v23 offset0:96 offset1:112
	ds_read2_b32 v[60:61], v62 offset0:64 offset1:80
	ds_read2_b32 v[62:63], v62 offset0:96 offset1:112
	s_waitcnt lgkmcnt(14)
	v_mov_b32_e32 v20, v26
	v_mov_b32_e32 v26, v28
	v_mov_b32_e32 v28, v30
	v_mov_b32_e32 v65, v32
	v_mov_b32_e32 v32, v21
	s_waitcnt lgkmcnt(11)
	v_mov_b32_e32 v21, v40
	v_mov_b32_e32 v40, v27
	s_waitcnt lgkmcnt(7)
	v_mov_b32_e32 v27, v48
	v_mov_b32_e32 v48, v29
	s_waitcnt lgkmcnt(4)
	v_mov_b32_e32 v29, v54
	v_mov_b32_e32 v54, v31
	v_mov_b32_e32 v30, v34
	v_mov_b32_e32 v31, v36
	v_mov_b32_e32 v36, v35
	v_mov_b32_e32 v34, v42
	v_mov_b32_e32 v42, v50
	s_waitcnt lgkmcnt(3)
	v_mov_b32_e32 v50, v56
	v_mov_b32_e32 v35, v44
	v_mov_b32_e32 v44, v43
	v_mov_b32_e32 v43, v52
	v_mov_b32_e32 v52, v51
	s_waitcnt lgkmcnt(2)
	v_mov_b32_e32 v51, v58
	v_mov_b32_e32 v58, v57
	v_add_u32_e32 v18, 0x200, v18
	s_waitcnt vmcnt(48)
	v_mov_b32_e32 v12, v186
	v_mov_b32_e32 v13, v187
	v_mov_b32_e32 v14, v188
	v_mov_b32_e32 v15, v189
	v_mov_b32_e32 v24, v190
	v_mov_b32_e32 v25, v191
	v_mov_b32_e32 v16, v192
	v_mov_b32_e32 v22, v193
	v_pk_fma_f32 v[10:11], v[12:13], v[64:65], v[10:11] op_sel_hi:[0,1,1]
	v_mov_b32_e32 v56, v13
	v_pk_fma_f32 v[8:9], v[12:13], v[30:31], v[8:9] op_sel_hi:[0,1,1]
	v_pk_mul_f32 v[38:39], v[12:13], v[38:39]
	v_pk_fma_f32 v[10:11], v[56:57], v[32:33], v[10:11] op_sel_hi:[0,1,1]
	v_pk_fma_f32 v[8:9], v[56:57], v[36:37], v[8:9] op_sel_hi:[0,1,1]
	v_add_f32_e32 v5, v5, v38
	v_add_f32_e32 v5, v5, v39
	v_pk_fma_f32 v[10:11], v[14:15], v[20:21], v[10:11] op_sel_hi:[0,1,1]
	v_mov_b32_e32 v20, v15
	v_pk_fma_f32 v[8:9], v[14:15], v[34:35], v[8:9] op_sel_hi:[0,1,1]
	v_pk_mul_f32 v[12:13], v[14:15], v[46:47]
	v_pk_fma_f32 v[10:11], v[20:21], v[40:41], v[10:11] op_sel_hi:[0,1,1]
	v_pk_fma_f32 v[8:9], v[20:21], v[44:45], v[8:9] op_sel_hi:[0,1,1]
	v_add_f32_e32 v5, v5, v12
	v_add_f32_e32 v5, v5, v13
	v_pk_fma_f32 v[10:11], v[24:25], v[26:27], v[10:11] op_sel_hi:[0,1,1]
	v_mov_b32_e32 v14, v25
	v_pk_fma_f32 v[8:9], v[24:25], v[42:43], v[8:9] op_sel_hi:[0,1,1]
	s_waitcnt lgkmcnt(1)
	v_pk_mul_f32 v[12:13], v[24:25], v[60:61]
	v_pk_fma_f32 v[10:11], v[14:15], v[48:49], v[10:11] op_sel_hi:[0,1,1]
	v_pk_fma_f32 v[8:9], v[14:15], v[52:53], v[8:9] op_sel_hi:[0,1,1]
	v_add_f32_e32 v5, v5, v12
	v_pk_fma_f32 v[10:11], v[16:17], v[28:29], v[10:11] op_sel_hi:[0,1,1]
	v_pk_fma_f32 v[8:9], v[16:17], v[50:51], v[8:9] op_sel_hi:[0,1,1]
	v_mov_b32_e32 v17, v22
	v_add_f32_e32 v5, v5, v13
	s_waitcnt lgkmcnt(0)
	v_pk_mul_f32 v[12:13], v[16:17], v[62:63]
	v_pk_fma_f32 v[10:11], v[22:23], v[54:55], v[10:11] op_sel_hi:[0,1,1]
	v_add_f32_e32 v5, v5, v12
	v_pk_fma_f32 v[8:9], v[22:23], v[58:59], v[8:9] op_sel_hi:[0,1,1]
	v_add_f32_e32 v5, v5, v13
	ds_read2_b32 v[20:21], v18 offset1:16
	v_add_u32_e32 v54, 0x1000, v18
	v_add_u32_e32 v62, 0x4000, v18
	s_waitcnt lgkmcnt(0)
	v_mov_b32_e32 v64, v20
	ds_read2_b32 v[26:27], v18 offset0:32 offset1:48
	ds_read2_b32 v[28:29], v18 offset0:64 offset1:80
	ds_read2_b32 v[30:31], v18 offset0:96 offset1:112
	v_add_u32_e32 v17, 0x2000, v18
	v_add_u32_e32 v23, 0x3000, v18
	ds_read2_b32 v[32:33], v54 offset1:16
	ds_read2_b32 v[34:35], v17 offset1:16
	ds_read2_b32 v[36:37], v23 offset1:16
	ds_read2_b32 v[38:39], v62 offset1:16
	ds_read2_b32 v[40:41], v54 offset0:32 offset1:48
	ds_read2_b32 v[42:43], v17 offset0:32 offset1:48
	ds_read2_b32 v[44:45], v23 offset0:32 offset1:48
	ds_read2_b32 v[46:47], v62 offset0:32 offset1:48
	ds_read2_b32 v[48:49], v54 offset0:64 offset1:80
	ds_read2_b32 v[50:51], v17 offset0:64 offset1:80
	ds_read2_b32 v[52:53], v23 offset0:64 offset1:80
	ds_read2_b32 v[54:55], v54 offset0:96 offset1:112
	ds_read2_b32 v[56:57], v17 offset0:96 offset1:112
	ds_read2_b32 v[58:59], v23 offset0:96 offset1:112
	ds_read2_b32 v[60:61], v62 offset0:64 offset1:80
	ds_read2_b32 v[62:63], v62 offset0:96 offset1:112
	s_waitcnt lgkmcnt(14)
	v_mov_b32_e32 v20, v26
	v_mov_b32_e32 v26, v28
	v_mov_b32_e32 v28, v30
	v_mov_b32_e32 v65, v32
	v_mov_b32_e32 v32, v21
	s_waitcnt lgkmcnt(11)
	v_mov_b32_e32 v21, v40
	v_mov_b32_e32 v40, v27
	s_waitcnt lgkmcnt(7)
	v_mov_b32_e32 v27, v48
	v_mov_b32_e32 v48, v29
	s_waitcnt lgkmcnt(4)
	v_mov_b32_e32 v29, v54
	v_mov_b32_e32 v54, v31
	v_mov_b32_e32 v30, v34
	v_mov_b32_e32 v31, v36
	v_mov_b32_e32 v36, v35
	v_mov_b32_e32 v34, v42
	v_mov_b32_e32 v42, v50
	s_waitcnt lgkmcnt(3)
	v_mov_b32_e32 v50, v56
	v_mov_b32_e32 v35, v44
	v_mov_b32_e32 v44, v43
	v_mov_b32_e32 v43, v52
	v_mov_b32_e32 v52, v51
	s_waitcnt lgkmcnt(2)
	v_mov_b32_e32 v51, v58
	v_mov_b32_e32 v58, v57
	v_add_u32_e32 v18, 0x200, v18
	s_waitcnt vmcnt(40)
	v_mov_b32_e32 v12, v194
	v_mov_b32_e32 v13, v195
	v_mov_b32_e32 v14, v196
	v_mov_b32_e32 v15, v197
	v_mov_b32_e32 v24, v198
	v_mov_b32_e32 v25, v199
	v_mov_b32_e32 v16, v200
	v_mov_b32_e32 v22, v201
	v_pk_fma_f32 v[10:11], v[12:13], v[64:65], v[10:11] op_sel_hi:[0,1,1]
	v_mov_b32_e32 v56, v13
	v_pk_fma_f32 v[8:9], v[12:13], v[30:31], v[8:9] op_sel_hi:[0,1,1]
	v_pk_mul_f32 v[38:39], v[12:13], v[38:39]
	v_pk_fma_f32 v[10:11], v[56:57], v[32:33], v[10:11] op_sel_hi:[0,1,1]
	v_pk_fma_f32 v[8:9], v[56:57], v[36:37], v[8:9] op_sel_hi:[0,1,1]
	v_add_f32_e32 v5, v5, v38
	v_add_f32_e32 v5, v5, v39
	v_pk_fma_f32 v[10:11], v[14:15], v[20:21], v[10:11] op_sel_hi:[0,1,1]
	v_mov_b32_e32 v20, v15
	v_pk_fma_f32 v[8:9], v[14:15], v[34:35], v[8:9] op_sel_hi:[0,1,1]
	v_pk_mul_f32 v[12:13], v[14:15], v[46:47]
	v_pk_fma_f32 v[10:11], v[20:21], v[40:41], v[10:11] op_sel_hi:[0,1,1]
	v_pk_fma_f32 v[8:9], v[20:21], v[44:45], v[8:9] op_sel_hi:[0,1,1]
	v_add_f32_e32 v5, v5, v12
	v_add_f32_e32 v5, v5, v13
	v_pk_fma_f32 v[10:11], v[24:25], v[26:27], v[10:11] op_sel_hi:[0,1,1]
	v_mov_b32_e32 v14, v25
	v_pk_fma_f32 v[8:9], v[24:25], v[42:43], v[8:9] op_sel_hi:[0,1,1]
	s_waitcnt lgkmcnt(1)
	v_pk_mul_f32 v[12:13], v[24:25], v[60:61]
	v_pk_fma_f32 v[10:11], v[14:15], v[48:49], v[10:11] op_sel_hi:[0,1,1]
	v_pk_fma_f32 v[8:9], v[14:15], v[52:53], v[8:9] op_sel_hi:[0,1,1]
	v_add_f32_e32 v5, v5, v12
	v_pk_fma_f32 v[10:11], v[16:17], v[28:29], v[10:11] op_sel_hi:[0,1,1]
	v_pk_fma_f32 v[8:9], v[16:17], v[50:51], v[8:9] op_sel_hi:[0,1,1]
	v_mov_b32_e32 v17, v22
	v_add_f32_e32 v5, v5, v13
	s_waitcnt lgkmcnt(0)
	v_pk_mul_f32 v[12:13], v[16:17], v[62:63]
	v_pk_fma_f32 v[10:11], v[22:23], v[54:55], v[10:11] op_sel_hi:[0,1,1]
	v_add_f32_e32 v5, v5, v12
	v_pk_fma_f32 v[8:9], v[22:23], v[58:59], v[8:9] op_sel_hi:[0,1,1]
	v_add_f32_e32 v5, v5, v13
	ds_read2_b32 v[20:21], v18 offset1:16
	v_add_u32_e32 v54, 0x1000, v18
	v_add_u32_e32 v62, 0x4000, v18
	s_waitcnt lgkmcnt(0)
	v_mov_b32_e32 v64, v20
	ds_read2_b32 v[26:27], v18 offset0:32 offset1:48
	ds_read2_b32 v[28:29], v18 offset0:64 offset1:80
	ds_read2_b32 v[30:31], v18 offset0:96 offset1:112
	v_add_u32_e32 v17, 0x2000, v18
	v_add_u32_e32 v23, 0x3000, v18
	ds_read2_b32 v[32:33], v54 offset1:16
	ds_read2_b32 v[34:35], v17 offset1:16
	ds_read2_b32 v[36:37], v23 offset1:16
	ds_read2_b32 v[38:39], v62 offset1:16
	ds_read2_b32 v[40:41], v54 offset0:32 offset1:48
	ds_read2_b32 v[42:43], v17 offset0:32 offset1:48
	ds_read2_b32 v[44:45], v23 offset0:32 offset1:48
	ds_read2_b32 v[46:47], v62 offset0:32 offset1:48
	ds_read2_b32 v[48:49], v54 offset0:64 offset1:80
	ds_read2_b32 v[50:51], v17 offset0:64 offset1:80
	ds_read2_b32 v[52:53], v23 offset0:64 offset1:80
	ds_read2_b32 v[54:55], v54 offset0:96 offset1:112
	ds_read2_b32 v[56:57], v17 offset0:96 offset1:112
	ds_read2_b32 v[58:59], v23 offset0:96 offset1:112
	ds_read2_b32 v[60:61], v62 offset0:64 offset1:80
	ds_read2_b32 v[62:63], v62 offset0:96 offset1:112
	s_waitcnt lgkmcnt(14)
	v_mov_b32_e32 v20, v26
	v_mov_b32_e32 v26, v28
	v_mov_b32_e32 v28, v30
	v_mov_b32_e32 v65, v32
	v_mov_b32_e32 v32, v21
	s_waitcnt lgkmcnt(11)
	v_mov_b32_e32 v21, v40
	v_mov_b32_e32 v40, v27
	s_waitcnt lgkmcnt(7)
	v_mov_b32_e32 v27, v48
	v_mov_b32_e32 v48, v29
	s_waitcnt lgkmcnt(4)
	v_mov_b32_e32 v29, v54
	v_mov_b32_e32 v54, v31
	v_mov_b32_e32 v30, v34
	v_mov_b32_e32 v31, v36
	v_mov_b32_e32 v36, v35
	v_mov_b32_e32 v34, v42
	v_mov_b32_e32 v42, v50
	s_waitcnt lgkmcnt(3)
	v_mov_b32_e32 v50, v56
	v_mov_b32_e32 v35, v44
	v_mov_b32_e32 v44, v43
	v_mov_b32_e32 v43, v52
	v_mov_b32_e32 v52, v51
	s_waitcnt lgkmcnt(2)
	v_mov_b32_e32 v51, v58
	v_mov_b32_e32 v58, v57
	v_add_u32_e32 v18, 0x200, v18
	s_waitcnt vmcnt(32)
	v_mov_b32_e32 v12, v204
	v_mov_b32_e32 v13, v205
	v_mov_b32_e32 v14, v206
	v_mov_b32_e32 v15, v207
	v_mov_b32_e32 v24, v208
	v_mov_b32_e32 v25, v209
	v_mov_b32_e32 v16, v210
	v_mov_b32_e32 v22, v211
	v_pk_fma_f32 v[10:11], v[12:13], v[64:65], v[10:11] op_sel_hi:[0,1,1]
	v_mov_b32_e32 v56, v13
	v_pk_fma_f32 v[8:9], v[12:13], v[30:31], v[8:9] op_sel_hi:[0,1,1]
	v_pk_mul_f32 v[38:39], v[12:13], v[38:39]
	v_pk_fma_f32 v[10:11], v[56:57], v[32:33], v[10:11] op_sel_hi:[0,1,1]
	v_pk_fma_f32 v[8:9], v[56:57], v[36:37], v[8:9] op_sel_hi:[0,1,1]
	v_add_f32_e32 v5, v5, v38
	v_add_f32_e32 v5, v5, v39
	v_pk_fma_f32 v[10:11], v[14:15], v[20:21], v[10:11] op_sel_hi:[0,1,1]
	v_mov_b32_e32 v20, v15
	v_pk_fma_f32 v[8:9], v[14:15], v[34:35], v[8:9] op_sel_hi:[0,1,1]
	v_pk_mul_f32 v[12:13], v[14:15], v[46:47]
	v_pk_fma_f32 v[10:11], v[20:21], v[40:41], v[10:11] op_sel_hi:[0,1,1]
	v_pk_fma_f32 v[8:9], v[20:21], v[44:45], v[8:9] op_sel_hi:[0,1,1]
	v_add_f32_e32 v5, v5, v12
	v_add_f32_e32 v5, v5, v13
	v_pk_fma_f32 v[10:11], v[24:25], v[26:27], v[10:11] op_sel_hi:[0,1,1]
	v_mov_b32_e32 v14, v25
	v_pk_fma_f32 v[8:9], v[24:25], v[42:43], v[8:9] op_sel_hi:[0,1,1]
	s_waitcnt lgkmcnt(1)
	v_pk_mul_f32 v[12:13], v[24:25], v[60:61]
	v_pk_fma_f32 v[10:11], v[14:15], v[48:49], v[10:11] op_sel_hi:[0,1,1]
	v_pk_fma_f32 v[8:9], v[14:15], v[52:53], v[8:9] op_sel_hi:[0,1,1]
	v_add_f32_e32 v5, v5, v12
	v_pk_fma_f32 v[10:11], v[16:17], v[28:29], v[10:11] op_sel_hi:[0,1,1]
	v_pk_fma_f32 v[8:9], v[16:17], v[50:51], v[8:9] op_sel_hi:[0,1,1]
	v_mov_b32_e32 v17, v22
	v_add_f32_e32 v5, v5, v13
	s_waitcnt lgkmcnt(0)
	v_pk_mul_f32 v[12:13], v[16:17], v[62:63]
	v_pk_fma_f32 v[10:11], v[22:23], v[54:55], v[10:11] op_sel_hi:[0,1,1]
	v_add_f32_e32 v5, v5, v12
	v_pk_fma_f32 v[8:9], v[22:23], v[58:59], v[8:9] op_sel_hi:[0,1,1]
	v_add_f32_e32 v5, v5, v13
	ds_read2_b32 v[20:21], v18 offset1:16
	v_add_u32_e32 v54, 0x1000, v18
	v_add_u32_e32 v62, 0x4000, v18
	s_waitcnt lgkmcnt(0)
	v_mov_b32_e32 v64, v20
	ds_read2_b32 v[26:27], v18 offset0:32 offset1:48
	ds_read2_b32 v[28:29], v18 offset0:64 offset1:80
	ds_read2_b32 v[30:31], v18 offset0:96 offset1:112
	v_add_u32_e32 v17, 0x2000, v18
	v_add_u32_e32 v23, 0x3000, v18
	ds_read2_b32 v[32:33], v54 offset1:16
	ds_read2_b32 v[34:35], v17 offset1:16
	ds_read2_b32 v[36:37], v23 offset1:16
	ds_read2_b32 v[38:39], v62 offset1:16
	ds_read2_b32 v[40:41], v54 offset0:32 offset1:48
	ds_read2_b32 v[42:43], v17 offset0:32 offset1:48
	ds_read2_b32 v[44:45], v23 offset0:32 offset1:48
	ds_read2_b32 v[46:47], v62 offset0:32 offset1:48
	ds_read2_b32 v[48:49], v54 offset0:64 offset1:80
	ds_read2_b32 v[50:51], v17 offset0:64 offset1:80
	ds_read2_b32 v[52:53], v23 offset0:64 offset1:80
	ds_read2_b32 v[54:55], v54 offset0:96 offset1:112
	ds_read2_b32 v[56:57], v17 offset0:96 offset1:112
	ds_read2_b32 v[58:59], v23 offset0:96 offset1:112
	ds_read2_b32 v[60:61], v62 offset0:64 offset1:80
	ds_read2_b32 v[62:63], v62 offset0:96 offset1:112
	s_waitcnt lgkmcnt(14)
	v_mov_b32_e32 v20, v26
	v_mov_b32_e32 v26, v28
	v_mov_b32_e32 v28, v30
	v_mov_b32_e32 v65, v32
	v_mov_b32_e32 v32, v21
	s_waitcnt lgkmcnt(11)
	v_mov_b32_e32 v21, v40
	v_mov_b32_e32 v40, v27
	s_waitcnt lgkmcnt(7)
	v_mov_b32_e32 v27, v48
	v_mov_b32_e32 v48, v29
	s_waitcnt lgkmcnt(4)
	v_mov_b32_e32 v29, v54
	v_mov_b32_e32 v54, v31
	v_mov_b32_e32 v30, v34
	v_mov_b32_e32 v31, v36
	v_mov_b32_e32 v36, v35
	v_mov_b32_e32 v34, v42
	v_mov_b32_e32 v42, v50
	s_waitcnt lgkmcnt(3)
	v_mov_b32_e32 v50, v56
	v_mov_b32_e32 v35, v44
	v_mov_b32_e32 v44, v43
	v_mov_b32_e32 v43, v52
	v_mov_b32_e32 v52, v51
	s_waitcnt lgkmcnt(2)
	v_mov_b32_e32 v51, v58
	v_mov_b32_e32 v58, v57
	v_add_u32_e32 v18, 0x200, v18
	s_waitcnt vmcnt(24)
	v_mov_b32_e32 v12, v212
	v_mov_b32_e32 v13, v213
	v_mov_b32_e32 v14, v214
	v_mov_b32_e32 v15, v215
	v_mov_b32_e32 v24, v216
	v_mov_b32_e32 v25, v217
	v_mov_b32_e32 v16, v218
	v_mov_b32_e32 v22, v219
	v_pk_fma_f32 v[10:11], v[12:13], v[64:65], v[10:11] op_sel_hi:[0,1,1]
	v_mov_b32_e32 v56, v13
	v_pk_fma_f32 v[8:9], v[12:13], v[30:31], v[8:9] op_sel_hi:[0,1,1]
	v_pk_mul_f32 v[38:39], v[12:13], v[38:39]
	v_pk_fma_f32 v[10:11], v[56:57], v[32:33], v[10:11] op_sel_hi:[0,1,1]
	v_pk_fma_f32 v[8:9], v[56:57], v[36:37], v[8:9] op_sel_hi:[0,1,1]
	v_add_f32_e32 v5, v5, v38
	v_add_f32_e32 v5, v5, v39
	v_pk_fma_f32 v[10:11], v[14:15], v[20:21], v[10:11] op_sel_hi:[0,1,1]
	v_mov_b32_e32 v20, v15
	v_pk_fma_f32 v[8:9], v[14:15], v[34:35], v[8:9] op_sel_hi:[0,1,1]
	v_pk_mul_f32 v[12:13], v[14:15], v[46:47]
	v_pk_fma_f32 v[10:11], v[20:21], v[40:41], v[10:11] op_sel_hi:[0,1,1]
	v_pk_fma_f32 v[8:9], v[20:21], v[44:45], v[8:9] op_sel_hi:[0,1,1]
	v_add_f32_e32 v5, v5, v12
	v_add_f32_e32 v5, v5, v13
	v_pk_fma_f32 v[10:11], v[24:25], v[26:27], v[10:11] op_sel_hi:[0,1,1]
	v_mov_b32_e32 v14, v25
	v_pk_fma_f32 v[8:9], v[24:25], v[42:43], v[8:9] op_sel_hi:[0,1,1]
	s_waitcnt lgkmcnt(1)
	v_pk_mul_f32 v[12:13], v[24:25], v[60:61]
	v_pk_fma_f32 v[10:11], v[14:15], v[48:49], v[10:11] op_sel_hi:[0,1,1]
	v_pk_fma_f32 v[8:9], v[14:15], v[52:53], v[8:9] op_sel_hi:[0,1,1]
	v_add_f32_e32 v5, v5, v12
	v_pk_fma_f32 v[10:11], v[16:17], v[28:29], v[10:11] op_sel_hi:[0,1,1]
	v_pk_fma_f32 v[8:9], v[16:17], v[50:51], v[8:9] op_sel_hi:[0,1,1]
	v_mov_b32_e32 v17, v22
	v_add_f32_e32 v5, v5, v13
	s_waitcnt lgkmcnt(0)
	v_pk_mul_f32 v[12:13], v[16:17], v[62:63]
	v_pk_fma_f32 v[10:11], v[22:23], v[54:55], v[10:11] op_sel_hi:[0,1,1]
	v_add_f32_e32 v5, v5, v12
	v_pk_fma_f32 v[8:9], v[22:23], v[58:59], v[8:9] op_sel_hi:[0,1,1]
	v_add_f32_e32 v5, v5, v13
	ds_read2_b32 v[20:21], v18 offset1:16
	v_add_u32_e32 v54, 0x1000, v18
	v_add_u32_e32 v62, 0x4000, v18
	s_waitcnt lgkmcnt(0)
	v_mov_b32_e32 v64, v20
	ds_read2_b32 v[26:27], v18 offset0:32 offset1:48
	ds_read2_b32 v[28:29], v18 offset0:64 offset1:80
	ds_read2_b32 v[30:31], v18 offset0:96 offset1:112
	v_add_u32_e32 v17, 0x2000, v18
	v_add_u32_e32 v23, 0x3000, v18
	ds_read2_b32 v[32:33], v54 offset1:16
	ds_read2_b32 v[34:35], v17 offset1:16
	ds_read2_b32 v[36:37], v23 offset1:16
	ds_read2_b32 v[38:39], v62 offset1:16
	ds_read2_b32 v[40:41], v54 offset0:32 offset1:48
	ds_read2_b32 v[42:43], v17 offset0:32 offset1:48
	ds_read2_b32 v[44:45], v23 offset0:32 offset1:48
	ds_read2_b32 v[46:47], v62 offset0:32 offset1:48
	ds_read2_b32 v[48:49], v54 offset0:64 offset1:80
	ds_read2_b32 v[50:51], v17 offset0:64 offset1:80
	ds_read2_b32 v[52:53], v23 offset0:64 offset1:80
	ds_read2_b32 v[54:55], v54 offset0:96 offset1:112
	ds_read2_b32 v[56:57], v17 offset0:96 offset1:112
	ds_read2_b32 v[58:59], v23 offset0:96 offset1:112
	ds_read2_b32 v[60:61], v62 offset0:64 offset1:80
	ds_read2_b32 v[62:63], v62 offset0:96 offset1:112
	s_waitcnt lgkmcnt(14)
	v_mov_b32_e32 v20, v26
	v_mov_b32_e32 v26, v28
	v_mov_b32_e32 v28, v30
	v_mov_b32_e32 v65, v32
	v_mov_b32_e32 v32, v21
	s_waitcnt lgkmcnt(11)
	v_mov_b32_e32 v21, v40
	v_mov_b32_e32 v40, v27
	s_waitcnt lgkmcnt(7)
	v_mov_b32_e32 v27, v48
	v_mov_b32_e32 v48, v29
	s_waitcnt lgkmcnt(4)
	v_mov_b32_e32 v29, v54
	v_mov_b32_e32 v54, v31
	v_mov_b32_e32 v30, v34
	v_mov_b32_e32 v31, v36
	v_mov_b32_e32 v36, v35
	v_mov_b32_e32 v34, v42
	v_mov_b32_e32 v42, v50
	s_waitcnt lgkmcnt(3)
	v_mov_b32_e32 v50, v56
	v_mov_b32_e32 v35, v44
	v_mov_b32_e32 v44, v43
	v_mov_b32_e32 v43, v52
	v_mov_b32_e32 v52, v51
	s_waitcnt lgkmcnt(2)
	v_mov_b32_e32 v51, v58
	v_mov_b32_e32 v58, v57
	v_add_u32_e32 v18, 0x200, v18
	s_waitcnt vmcnt(16)
	v_mov_b32_e32 v12, v220
	v_mov_b32_e32 v13, v221
	v_mov_b32_e32 v14, v222
	v_mov_b32_e32 v15, v223
	v_mov_b32_e32 v24, v224
	v_mov_b32_e32 v25, v225
	v_mov_b32_e32 v16, v226
	v_mov_b32_e32 v22, v227
	v_pk_fma_f32 v[10:11], v[12:13], v[64:65], v[10:11] op_sel_hi:[0,1,1]
	v_mov_b32_e32 v56, v13
	v_pk_fma_f32 v[8:9], v[12:13], v[30:31], v[8:9] op_sel_hi:[0,1,1]
	v_pk_mul_f32 v[38:39], v[12:13], v[38:39]
	v_pk_fma_f32 v[10:11], v[56:57], v[32:33], v[10:11] op_sel_hi:[0,1,1]
	v_pk_fma_f32 v[8:9], v[56:57], v[36:37], v[8:9] op_sel_hi:[0,1,1]
	v_add_f32_e32 v5, v5, v38
	v_add_f32_e32 v5, v5, v39
	v_pk_fma_f32 v[10:11], v[14:15], v[20:21], v[10:11] op_sel_hi:[0,1,1]
	v_mov_b32_e32 v20, v15
	v_pk_fma_f32 v[8:9], v[14:15], v[34:35], v[8:9] op_sel_hi:[0,1,1]
	v_pk_mul_f32 v[12:13], v[14:15], v[46:47]
	v_pk_fma_f32 v[10:11], v[20:21], v[40:41], v[10:11] op_sel_hi:[0,1,1]
	v_pk_fma_f32 v[8:9], v[20:21], v[44:45], v[8:9] op_sel_hi:[0,1,1]
	v_add_f32_e32 v5, v5, v12
	v_add_f32_e32 v5, v5, v13
	v_pk_fma_f32 v[10:11], v[24:25], v[26:27], v[10:11] op_sel_hi:[0,1,1]
	v_mov_b32_e32 v14, v25
	v_pk_fma_f32 v[8:9], v[24:25], v[42:43], v[8:9] op_sel_hi:[0,1,1]
	s_waitcnt lgkmcnt(1)
	v_pk_mul_f32 v[12:13], v[24:25], v[60:61]
	v_pk_fma_f32 v[10:11], v[14:15], v[48:49], v[10:11] op_sel_hi:[0,1,1]
	v_pk_fma_f32 v[8:9], v[14:15], v[52:53], v[8:9] op_sel_hi:[0,1,1]
	v_add_f32_e32 v5, v5, v12
	v_pk_fma_f32 v[10:11], v[16:17], v[28:29], v[10:11] op_sel_hi:[0,1,1]
	v_pk_fma_f32 v[8:9], v[16:17], v[50:51], v[8:9] op_sel_hi:[0,1,1]
	v_mov_b32_e32 v17, v22
	v_add_f32_e32 v5, v5, v13
	s_waitcnt lgkmcnt(0)
	v_pk_mul_f32 v[12:13], v[16:17], v[62:63]
	v_pk_fma_f32 v[10:11], v[22:23], v[54:55], v[10:11] op_sel_hi:[0,1,1]
	v_add_f32_e32 v5, v5, v12
	v_pk_fma_f32 v[8:9], v[22:23], v[58:59], v[8:9] op_sel_hi:[0,1,1]
	v_add_f32_e32 v5, v5, v13
	ds_read2_b32 v[20:21], v18 offset1:16
	v_add_u32_e32 v54, 0x1000, v18
	v_add_u32_e32 v62, 0x4000, v18
	s_waitcnt lgkmcnt(0)
	v_mov_b32_e32 v64, v20
	ds_read2_b32 v[26:27], v18 offset0:32 offset1:48
	ds_read2_b32 v[28:29], v18 offset0:64 offset1:80
	ds_read2_b32 v[30:31], v18 offset0:96 offset1:112
	v_add_u32_e32 v17, 0x2000, v18
	v_add_u32_e32 v23, 0x3000, v18
	ds_read2_b32 v[32:33], v54 offset1:16
	ds_read2_b32 v[34:35], v17 offset1:16
	ds_read2_b32 v[36:37], v23 offset1:16
	ds_read2_b32 v[38:39], v62 offset1:16
	ds_read2_b32 v[40:41], v54 offset0:32 offset1:48
	ds_read2_b32 v[42:43], v17 offset0:32 offset1:48
	ds_read2_b32 v[44:45], v23 offset0:32 offset1:48
	ds_read2_b32 v[46:47], v62 offset0:32 offset1:48
	ds_read2_b32 v[48:49], v54 offset0:64 offset1:80
	ds_read2_b32 v[50:51], v17 offset0:64 offset1:80
	ds_read2_b32 v[52:53], v23 offset0:64 offset1:80
	ds_read2_b32 v[54:55], v54 offset0:96 offset1:112
	ds_read2_b32 v[56:57], v17 offset0:96 offset1:112
	ds_read2_b32 v[58:59], v23 offset0:96 offset1:112
	ds_read2_b32 v[60:61], v62 offset0:64 offset1:80
	ds_read2_b32 v[62:63], v62 offset0:96 offset1:112
	s_waitcnt lgkmcnt(14)
	v_mov_b32_e32 v20, v26
	v_mov_b32_e32 v26, v28
	v_mov_b32_e32 v28, v30
	v_mov_b32_e32 v65, v32
	v_mov_b32_e32 v32, v21
	s_waitcnt lgkmcnt(11)
	v_mov_b32_e32 v21, v40
	v_mov_b32_e32 v40, v27
	s_waitcnt lgkmcnt(7)
	v_mov_b32_e32 v27, v48
	v_mov_b32_e32 v48, v29
	s_waitcnt lgkmcnt(4)
	v_mov_b32_e32 v29, v54
	v_mov_b32_e32 v54, v31
	v_mov_b32_e32 v30, v34
	v_mov_b32_e32 v31, v36
	v_mov_b32_e32 v36, v35
	v_mov_b32_e32 v34, v42
	v_mov_b32_e32 v42, v50
	s_waitcnt lgkmcnt(3)
	v_mov_b32_e32 v50, v56
	v_mov_b32_e32 v35, v44
	v_mov_b32_e32 v44, v43
	v_mov_b32_e32 v43, v52
	v_mov_b32_e32 v52, v51
	s_waitcnt lgkmcnt(2)
	v_mov_b32_e32 v51, v58
	v_mov_b32_e32 v58, v57
	v_add_u32_e32 v18, 0x200, v18
	s_waitcnt vmcnt(8)
	v_mov_b32_e32 v12, v228
	v_mov_b32_e32 v13, v229
	v_mov_b32_e32 v14, v230
	v_mov_b32_e32 v15, v231
	v_mov_b32_e32 v24, v232
	v_mov_b32_e32 v25, v233
	v_mov_b32_e32 v16, v234
	v_mov_b32_e32 v22, v235
	v_pk_fma_f32 v[10:11], v[12:13], v[64:65], v[10:11] op_sel_hi:[0,1,1]
	v_mov_b32_e32 v56, v13
	v_pk_fma_f32 v[8:9], v[12:13], v[30:31], v[8:9] op_sel_hi:[0,1,1]
	v_pk_mul_f32 v[38:39], v[12:13], v[38:39]
	v_pk_fma_f32 v[10:11], v[56:57], v[32:33], v[10:11] op_sel_hi:[0,1,1]
	v_pk_fma_f32 v[8:9], v[56:57], v[36:37], v[8:9] op_sel_hi:[0,1,1]
	v_add_f32_e32 v5, v5, v38
	v_add_f32_e32 v5, v5, v39
	v_pk_fma_f32 v[10:11], v[14:15], v[20:21], v[10:11] op_sel_hi:[0,1,1]
	v_mov_b32_e32 v20, v15
	v_pk_fma_f32 v[8:9], v[14:15], v[34:35], v[8:9] op_sel_hi:[0,1,1]
	v_pk_mul_f32 v[12:13], v[14:15], v[46:47]
	v_pk_fma_f32 v[10:11], v[20:21], v[40:41], v[10:11] op_sel_hi:[0,1,1]
	v_pk_fma_f32 v[8:9], v[20:21], v[44:45], v[8:9] op_sel_hi:[0,1,1]
	v_add_f32_e32 v5, v5, v12
	v_add_f32_e32 v5, v5, v13
	v_pk_fma_f32 v[10:11], v[24:25], v[26:27], v[10:11] op_sel_hi:[0,1,1]
	v_mov_b32_e32 v14, v25
	v_pk_fma_f32 v[8:9], v[24:25], v[42:43], v[8:9] op_sel_hi:[0,1,1]
	s_waitcnt lgkmcnt(1)
	v_pk_mul_f32 v[12:13], v[24:25], v[60:61]
	v_pk_fma_f32 v[10:11], v[14:15], v[48:49], v[10:11] op_sel_hi:[0,1,1]
	v_pk_fma_f32 v[8:9], v[14:15], v[52:53], v[8:9] op_sel_hi:[0,1,1]
	v_add_f32_e32 v5, v5, v12
	v_pk_fma_f32 v[10:11], v[16:17], v[28:29], v[10:11] op_sel_hi:[0,1,1]
	v_pk_fma_f32 v[8:9], v[16:17], v[50:51], v[8:9] op_sel_hi:[0,1,1]
	v_mov_b32_e32 v17, v22
	v_add_f32_e32 v5, v5, v13
	s_waitcnt lgkmcnt(0)
	v_pk_mul_f32 v[12:13], v[16:17], v[62:63]
	v_pk_fma_f32 v[10:11], v[22:23], v[54:55], v[10:11] op_sel_hi:[0,1,1]
	v_add_f32_e32 v5, v5, v12
	v_pk_fma_f32 v[8:9], v[22:23], v[58:59], v[8:9] op_sel_hi:[0,1,1]
	v_add_f32_e32 v5, v5, v13
	ds_read2_b32 v[20:21], v18 offset1:16
	v_add_u32_e32 v54, 0x1000, v18
	v_add_u32_e32 v62, 0x4000, v18
	s_waitcnt lgkmcnt(0)
	v_mov_b32_e32 v64, v20
	ds_read2_b32 v[26:27], v18 offset0:32 offset1:48
	ds_read2_b32 v[28:29], v18 offset0:64 offset1:80
	ds_read2_b32 v[30:31], v18 offset0:96 offset1:112
	v_add_u32_e32 v17, 0x2000, v18
	v_add_u32_e32 v23, 0x3000, v18
	ds_read2_b32 v[32:33], v54 offset1:16
	ds_read2_b32 v[34:35], v17 offset1:16
	ds_read2_b32 v[36:37], v23 offset1:16
	ds_read2_b32 v[38:39], v62 offset1:16
	ds_read2_b32 v[40:41], v54 offset0:32 offset1:48
	ds_read2_b32 v[42:43], v17 offset0:32 offset1:48
	ds_read2_b32 v[44:45], v23 offset0:32 offset1:48
	ds_read2_b32 v[46:47], v62 offset0:32 offset1:48
	ds_read2_b32 v[48:49], v54 offset0:64 offset1:80
	ds_read2_b32 v[50:51], v17 offset0:64 offset1:80
	ds_read2_b32 v[52:53], v23 offset0:64 offset1:80
	ds_read2_b32 v[54:55], v54 offset0:96 offset1:112
	ds_read2_b32 v[56:57], v17 offset0:96 offset1:112
	ds_read2_b32 v[58:59], v23 offset0:96 offset1:112
	ds_read2_b32 v[60:61], v62 offset0:64 offset1:80
	ds_read2_b32 v[62:63], v62 offset0:96 offset1:112
	s_waitcnt lgkmcnt(14)
	v_mov_b32_e32 v20, v26
	v_mov_b32_e32 v26, v28
	v_mov_b32_e32 v28, v30
	v_mov_b32_e32 v65, v32
	v_mov_b32_e32 v32, v21
	s_waitcnt lgkmcnt(11)
	v_mov_b32_e32 v21, v40
	v_mov_b32_e32 v40, v27
	s_waitcnt lgkmcnt(7)
	v_mov_b32_e32 v27, v48
	v_mov_b32_e32 v48, v29
	s_waitcnt lgkmcnt(4)
	v_mov_b32_e32 v29, v54
	v_mov_b32_e32 v54, v31
	v_mov_b32_e32 v30, v34
	v_mov_b32_e32 v31, v36
	v_mov_b32_e32 v36, v35
	v_mov_b32_e32 v34, v42
	v_mov_b32_e32 v42, v50
	s_waitcnt lgkmcnt(3)
	v_mov_b32_e32 v50, v56
	v_mov_b32_e32 v35, v44
	v_mov_b32_e32 v44, v43
	v_mov_b32_e32 v43, v52
	v_mov_b32_e32 v52, v51
	s_waitcnt lgkmcnt(2)
	v_mov_b32_e32 v51, v58
	v_mov_b32_e32 v58, v57
	v_add_u32_e32 v18, 0x200, v18
	s_waitcnt vmcnt(0)
	v_mov_b32_e32 v12, v236
	v_mov_b32_e32 v13, v237
	v_mov_b32_e32 v14, v238
	v_mov_b32_e32 v15, v239
	v_mov_b32_e32 v24, v240
	v_mov_b32_e32 v25, v241
	v_mov_b32_e32 v16, v242
	v_mov_b32_e32 v22, v243
	v_pk_fma_f32 v[10:11], v[12:13], v[64:65], v[10:11] op_sel_hi:[0,1,1]
	v_mov_b32_e32 v56, v13
	v_pk_fma_f32 v[8:9], v[12:13], v[30:31], v[8:9] op_sel_hi:[0,1,1]
	v_pk_mul_f32 v[38:39], v[12:13], v[38:39]
	v_pk_fma_f32 v[10:11], v[56:57], v[32:33], v[10:11] op_sel_hi:[0,1,1]
	v_pk_fma_f32 v[8:9], v[56:57], v[36:37], v[8:9] op_sel_hi:[0,1,1]
	v_add_f32_e32 v5, v5, v38
	v_add_f32_e32 v5, v5, v39
	v_pk_fma_f32 v[10:11], v[14:15], v[20:21], v[10:11] op_sel_hi:[0,1,1]
	v_mov_b32_e32 v20, v15
	v_pk_fma_f32 v[8:9], v[14:15], v[34:35], v[8:9] op_sel_hi:[0,1,1]
	v_pk_mul_f32 v[12:13], v[14:15], v[46:47]
	v_pk_fma_f32 v[10:11], v[20:21], v[40:41], v[10:11] op_sel_hi:[0,1,1]
	v_pk_fma_f32 v[8:9], v[20:21], v[44:45], v[8:9] op_sel_hi:[0,1,1]
	v_add_f32_e32 v5, v5, v12
	v_add_f32_e32 v5, v5, v13
	v_pk_fma_f32 v[10:11], v[24:25], v[26:27], v[10:11] op_sel_hi:[0,1,1]
	v_mov_b32_e32 v14, v25
	v_pk_fma_f32 v[8:9], v[24:25], v[42:43], v[8:9] op_sel_hi:[0,1,1]
	s_waitcnt lgkmcnt(1)
	v_pk_mul_f32 v[12:13], v[24:25], v[60:61]
	v_pk_fma_f32 v[10:11], v[14:15], v[48:49], v[10:11] op_sel_hi:[0,1,1]
	v_pk_fma_f32 v[8:9], v[14:15], v[52:53], v[8:9] op_sel_hi:[0,1,1]
	v_add_f32_e32 v5, v5, v12
	v_pk_fma_f32 v[10:11], v[16:17], v[28:29], v[10:11] op_sel_hi:[0,1,1]
	v_pk_fma_f32 v[8:9], v[16:17], v[50:51], v[8:9] op_sel_hi:[0,1,1]
	v_mov_b32_e32 v17, v22
	v_add_f32_e32 v5, v5, v13
	s_waitcnt lgkmcnt(0)
	v_pk_mul_f32 v[12:13], v[16:17], v[62:63]
	v_pk_fma_f32 v[10:11], v[22:23], v[54:55], v[10:11] op_sel_hi:[0,1,1]
	v_add_f32_e32 v5, v5, v12
	v_pk_fma_f32 v[8:9], v[22:23], v[58:59], v[8:9] op_sel_hi:[0,1,1]
	v_add_f32_e32 v5, v5, v13
	s_or_b64 exec, exec, s[4:5]

.LBB0_260:
	s_cmp_lt_u32 s74, 32
	s_cbranch_scc1 .Lmy_nodelay2
	s_lshr_b32 s98, s74, 3
	s_and_b32 s98, s98, 1
	s_cmp_eq_u32 s98, 0
	s_cbranch_scc1 .Lmy_nodelay2
.Lmy_delay2:
	s_sleep 64
	s_sleep 64
	s_sleep 64
	s_sleep 64
	s_sleep 64
	s_sleep 64
	s_sub_u32 s98, s98, 1
	s_cmp_lg_u32 s98, 0
	s_cbranch_scc1 .Lmy_delay2

	.amdhsa_kernel _Z10fwd_kernel6Params
		.amdhsa_group_segment_fixed_size 0
		.amdhsa_private_segment_fixed_size 0
		.amdhsa_kernarg_size 496
		.amdhsa_user_sgpr_count 2
		.amdhsa_user_sgpr_dispatch_ptr 0
		.amdhsa_user_sgpr_queue_ptr 0
		.amdhsa_user_sgpr_kernarg_segment_ptr 1
		.amdhsa_user_sgpr_dispatch_id 0
		.amdhsa_user_sgpr_kernarg_preload_length 0
		.amdhsa_user_sgpr_kernarg_preload_offset 0
		.amdhsa_user_sgpr_private_segment_size 0
		.amdhsa_uses_dynamic_stack 0
		.amdhsa_enable_private_segment 0
		.amdhsa_system_sgpr_workgroup_id_x 1
		.amdhsa_system_sgpr_workgroup_id_y 0
		.amdhsa_system_sgpr_workgroup_id_z 0
		.amdhsa_system_sgpr_workgroup_info 0
		.amdhsa_system_vgpr_workitem_id 2
		.amdhsa_next_free_vgpr 256
		.amdhsa_next_free_sgpr 102
		.amdhsa_accum_offset 256
		.amdhsa_reserve_vcc 1
		.amdhsa_float_round_mode_32 0
		.amdhsa_float_round_mode_16_64 0
		.amdhsa_float_denorm_mode_32 3
		.amdhsa_float_denorm_mode_16_64 3
		.amdhsa_dx10_clamp 1
		.amdhsa_ieee_mode 1
		.amdhsa_fp16_overflow 0
		.amdhsa_tg_split 0
		.amdhsa_exception_fp_ieee_invalid_op 0
		.amdhsa_exception_fp_denorm_src 0
		.amdhsa_exception_fp_ieee_div_zero 0
		.amdhsa_exception_fp_ieee_overflow 0
		.amdhsa_exception_fp_ieee_underflow 0
		.amdhsa_exception_fp_ieee_inexact 0
		.amdhsa_exception_int_div_zero 0
	.end_amdhsa_kernel

amdhsa.kernels:
  - .agpr_count:     0
    .args:
      - .offset:         0
        .size:           240
        .value_kind:     by_value
      - .offset:         240
        .size:           4
        .value_kind:     hidden_block_count_x
      - .offset:         244
        .size:           4
        .value_kind:     hidden_block_count_y
      - .offset:         248
        .size:           4
        .value_kind:     hidden_block_count_z
      - .offset:         252
        .size:           2
        .value_kind:     hidden_group_size_x
      - .offset:         254
        .size:           2
        .value_kind:     hidden_group_size_y
      - .offset:         256
        .size:           2
        .value_kind:     hidden_group_size_z
      - .offset:         258
        .size:           2
        .value_kind:     hidden_remainder_x
      - .offset:         260
        .size:           2
        .value_kind:     hidden_remainder_y
      - .offset:         262
        .size:           2
        .value_kind:     hidden_remainder_z
      - .offset:         280
        .size:           8
        .value_kind:     hidden_global_offset_x
      - .offset:         288
        .size:           8
        .value_kind:     hidden_global_offset_y
      - .offset:         296
        .size:           8
        .value_kind:     hidden_global_offset_z
      - .offset:         304
        .size:           2
        .value_kind:     hidden_grid_dims
      - .offset:         328
        .size:           8
        .value_kind:     hidden_multigrid_sync_arg
      - .offset:         360
        .size:           4
        .value_kind:     hidden_dynamic_lds_size
    .group_segment_fixed_size: 0
    .kernarg_segment_align: 8
    .kernarg_segment_size: 496
    .language:       OpenCL C
    .language_version:
      - 2
      - 0
    .max_flat_workgroup_size: 512
    .name:           _Z10fwd_kernel6Params
    .private_segment_fixed_size: 0
    .sgpr_count:     108
    .sgpr_spill_count: 183
    .symbol:         _Z10fwd_kernel6Params.kd
    .uniform_work_group_size: 1
    .uses_dynamic_stack: false
    .vgpr_count:     256
    .vgpr_spill_count: 0
    .wavefront_size: 64
